# lever 8 variant: LDS read-ahead distance 13 in the scan phases 7 and 14
# baseline (speedup 1.0000x reference)
.LBB0_1046:
	v_mov_b32_e32 v37, v34
	v_mov_b32_e32 v34, v33
	v_mov_b32_e32 v36, v32
	v_pk_mul_f32 v[32:33], v[80:81], v[34:35]
	v_mov_b32_e32 v34, v38
	v_mov_b32_e32 v35, v40
	v_pk_mul_f32 v[36:37], v[80:81], v[36:37]
	v_pk_mul_f32 v[34:35], v[80:81], v[34:35]
	v_cvt_pk_bf16_f32 v36, v36, v37
	v_mov_b32_e32 v40, v39
	v_cvt_pk_bf16_f32 v37, v34, v35
	v_mov_b32_e32 v34, v42
	v_mov_b32_e32 v35, v44
	v_mov_b32_e32 v44, v43
	v_pk_mul_f32 v[38:39], v[80:81], v[40:41]
	v_pk_mul_f32 v[34:35], v[80:81], v[34:35]
	v_pk_mul_f32 v[40:41], v[80:81], v[44:45]
	v_cvt_pk_bf16_f32 v32, v32, v33
	v_cvt_pk_bf16_f32 v33, v38, v39
	v_cvt_pk_bf16_f32 v38, v34, v35
	v_cvt_pk_bf16_f32 v34, v40, v41
	v_mov_b32_e32 v40, v46
	v_mov_b32_e32 v41, v48
	v_pk_mul_f32 v[40:41], v[80:81], v[40:41]
	v_mov_b32_e32 v48, v47
	v_pk_mul_f32 v[42:43], v[80:81], v[48:49]
	v_cvt_pk_bf16_f32 v39, v40, v41
	v_mov_b32_e32 v40, v50
	v_mov_b32_e32 v41, v52
	v_mov_b32_e32 v52, v51
	v_cvt_pk_bf16_f32 v35, v42, v43
	v_pk_mul_f32 v[40:41], v[80:81], v[40:41]
	v_pk_mul_f32 v[42:43], v[80:81], v[52:53]
	v_cvt_pk_bf16_f32 v44, v40, v41
	v_cvt_pk_bf16_f32 v40, v42, v43
	v_mov_b32_e32 v42, v54
	v_mov_b32_e32 v43, v56
	v_pk_mul_f32 v[42:43], v[80:81], v[42:43]
	v_mov_b32_e32 v56, v55
	v_cvt_pk_bf16_f32 v45, v42, v43
	v_mov_b32_e32 v42, v58
	v_mov_b32_e32 v43, v60
	v_mov_b32_e32 v60, v59
	v_pk_mul_f32 v[46:47], v[80:81], v[56:57]
	v_pk_mul_f32 v[42:43], v[80:81], v[42:43]
	v_pk_mul_f32 v[48:49], v[80:81], v[60:61]
	v_cvt_pk_bf16_f32 v41, v46, v47
	v_cvt_pk_bf16_f32 v46, v42, v43
	v_cvt_pk_bf16_f32 v42, v48, v49
	v_mov_b32_e32 v48, v62
	v_mov_b32_e32 v49, v90
	v_mov_b32_e32 v90, v63
	v_pk_mul_f32 v[48:49], v[80:81], v[48:49]
	v_pk_mul_f32 v[50:51], v[80:81], v[90:91]
	v_cvt_pk_bf16_f32 v47, v48, v49
	v_cvt_pk_bf16_f32 v43, v50, v51
	s_waitcnt lgkmcnt(0)
	s_barrier
	s_waitcnt lgkmcnt(0)
	ds_read_b128 v[196:199], v97
	v_add_u32_e32 v52, v98, v100
	s_add_i32 s50, s50, -1
	s_add_i32 s54, s54, 1
	s_cmp_lg_u32 s50, -2
	s_waitcnt lgkmcnt(0)
	v_pk_mul_f32 v[48:49], v[4:5], v[196:197]
	v_pk_mul_f32 v[50:51], v[6:7], v[198:199]
	v_cvt_pk_bf16_f32 v48, v48, v49
	v_cvt_pk_bf16_f32 v49, v50, v51
	ds_write_b64 v52, v[48:49] offset:45056
	ds_read_b128 v[200:203], v97 offset:64
	s_waitcnt lgkmcnt(0)
	v_pk_mul_f32 v[48:49], v[0:1], v[200:201]
	v_pk_mul_f32 v[50:51], v[2:3], v[202:203]
	v_cvt_pk_bf16_f32 v48, v48, v49
	v_cvt_pk_bf16_f32 v49, v50, v51
	ds_write_b64 v123, v[48:49] offset:45056
	ds_read_b128 v[204:207], v97 offset:128
	s_waitcnt lgkmcnt(0)
	v_pk_mul_f32 v[48:49], v[8:9], v[204:205]
	v_pk_mul_f32 v[50:51], v[10:11], v[206:207]
	v_cvt_pk_bf16_f32 v48, v48, v49
	v_cvt_pk_bf16_f32 v49, v50, v51
	ds_write_b64 v124, v[48:49] offset:45056
	ds_read_b128 v[208:211], v97 offset:192
	s_waitcnt lgkmcnt(0)
	v_pk_mul_f32 v[48:49], v[12:13], v[208:209]
	v_pk_mul_f32 v[50:51], v[14:15], v[210:211]
	v_cvt_pk_bf16_f32 v48, v48, v49
	v_cvt_pk_bf16_f32 v49, v50, v51
	ds_write_b64 v125, v[48:49] offset:45056
	ds_read_b128 v[212:215], v97 offset:256
	s_waitcnt lgkmcnt(0)
	v_pk_mul_f32 v[48:49], v[16:17], v[212:213]
	v_pk_mul_f32 v[50:51], v[18:19], v[214:215]
	v_cvt_pk_bf16_f32 v48, v48, v49
	v_cvt_pk_bf16_f32 v49, v50, v51
	ds_write_b64 v52, v[48:49] offset:45184
	ds_read_b128 v[216:219], v97 offset:320
	s_waitcnt lgkmcnt(0)
	v_pk_mul_f32 v[48:49], v[20:21], v[216:217]
	v_pk_mul_f32 v[50:51], v[22:23], v[218:219]
	v_cvt_pk_bf16_f32 v48, v48, v49
	v_cvt_pk_bf16_f32 v49, v50, v51
	ds_write_b64 v52, v[48:49] offset:45216
	ds_read_b128 v[220:223], v97 offset:384
	s_waitcnt lgkmcnt(0)
	v_pk_mul_f32 v[48:49], v[24:25], v[220:221]
	v_pk_mul_f32 v[50:51], v[26:27], v[222:223]
	v_cvt_pk_bf16_f32 v48, v48, v49
	v_cvt_pk_bf16_f32 v49, v50, v51
	ds_write_b64 v52, v[48:49] offset:45248
	ds_read_b128 v[224:227], v97 offset:448
	s_waitcnt lgkmcnt(0)
	v_pk_mul_f32 v[48:49], v[28:29], v[224:225]
	v_pk_mul_f32 v[50:51], v[30:31], v[226:227]
	v_cvt_pk_bf16_f32 v48, v48, v49
	v_cvt_pk_bf16_f32 v49, v50, v51
	ds_write_b64 v52, v[48:49] offset:45280
	ds_read_b128 v[228:231], v126 offset:17408
	ds_read_b128 v[232:235], v126 offset:17472
	ds_read_b128 v[236:239], v126 offset:17536
	ds_read_b128 v[244:247], v126 offset:17600
	ds_read_b128 v[248:251], v126 offset:21824
	ds_read_b128 v[252:255], v126 offset:21760
	ds_read_b128 v[196:199], v126 offset:21888
	ds_read_b128 v[200:203], v126 offset:21952
	ds_read_b128 v[204:207], v126 offset:26176
	ds_read_b128 v[208:211], v126 offset:26112
	ds_read_b128 v[212:215], v126 offset:26240
	ds_read_b128 v[216:219], v126 offset:26304
	ds_read_b128 v[220:223], v126 offset:30528
	v_add_u32_e32 v48, v98, v96
	ds_read_b128 v[60:63], v48
	ds_read_b128 v[52:55], v48 offset:64
	ds_read_b128 v[56:59], v48 offset:128
	ds_read_b128 v[48:51], v48 offset:192
	s_waitcnt lgkmcnt(3)
	v_mfma_f32_16x16x32_bf16 v[172:175], v[228:231], v[60:63], 0
	ds_read_b128 v[224:227], v126 offset:30464
	s_waitcnt lgkmcnt(3)
	v_mfma_f32_16x16x32_bf16 v[172:175], v[232:235], v[52:55], v[172:175]
	ds_read_b128 v[228:231], v126 offset:30592
	s_waitcnt lgkmcnt(3)
	v_mfma_f32_16x16x32_bf16 v[172:175], v[236:239], v[56:59], v[172:175]
	s_waitcnt lgkmcnt(2)
	v_mfma_f32_16x16x32_bf16 v[172:175], v[244:247], v[48:51], v[172:175]
	s_nop 6
	s_nop 0
	v_cndmask_b32_e64 v64, v172, 0, s[2:3]
	v_cndmask_b32_e64 v77, v173, 0, s[4:5]
	v_cndmask_b32_e64 v89, v174, 0, s[6:7]
	v_cndmask_b32_e64 v91, v175, 0, s[8:9]
	v_mfma_f32_16x16x32_bf16 v[172:175], v[252:255], v[60:63], 0
	v_cvt_pk_bf16_f32 v90, v64, v77
	v_cvt_pk_bf16_f32 v91, v89, v91
	v_mfma_f32_16x16x32_bf16 v[172:175], v[248:251], v[52:55], v[172:175]
	v_mfma_f32_16x16x32_bf16 v[172:175], v[196:199], v[56:59], v[172:175]
	v_mfma_f32_16x16x32_bf16 v[172:175], v[200:203], v[48:51], v[172:175]
	s_nop 6
	s_nop 0
	v_cndmask_b32_e64 v64, v172, 0, s[10:11]
	v_cndmask_b32_e64 v89, v174, 0, s[14:15]
	v_cndmask_b32_e64 v172, v175, 0, s[16:17]
	v_cndmask_b32_e64 v77, v173, 0, s[12:13]
	v_cvt_pk_bf16_f32 v177, v89, v172
	v_mfma_f32_16x16x32_bf16 v[172:175], v[208:211], v[60:63], 0
	v_cvt_pk_bf16_f32 v176, v64, v77
	v_mfma_f32_16x16x32_bf16 v[172:175], v[204:207], v[52:55], v[172:175]
	v_mfma_f32_16x16x32_bf16 v[172:175], v[212:215], v[56:59], v[172:175]
	v_mfma_f32_16x16x32_bf16 v[172:175], v[216:219], v[48:51], v[172:175]
	s_nop 6
	s_nop 0
	v_cndmask_b32_e64 v64, v172, 0, s[18:19]
	v_cndmask_b32_e64 v89, v174, 0, s[22:23]
	v_cndmask_b32_e64 v172, v175, 0, s[24:25]
	v_cndmask_b32_e64 v77, v173, 0, s[20:21]
	v_cvt_pk_bf16_f32 v193, v89, v172
	s_waitcnt lgkmcnt(1)
	v_mfma_f32_16x16x32_bf16 v[172:175], v[224:227], v[60:63], 0
	v_cvt_pk_bf16_f32 v192, v64, v77
	v_mfma_f32_16x16x32_bf16 v[172:175], v[220:223], v[52:55], v[172:175]
	s_waitcnt lgkmcnt(0)
	v_mfma_f32_16x16x32_bf16 v[172:175], v[228:231], v[56:59], v[172:175]
	ds_read_b128 v[188:191], v126 offset:30656
	s_waitcnt lgkmcnt(0)
	s_barrier
	v_mfma_f32_16x16x32_bf16 v[172:175], v[188:191], v[48:51], v[172:175]
	s_nop 7
	v_cndmask_b32_e64 v64, v172, 0, s[26:27]
	v_cndmask_b32_e64 v77, v173, 0, s[28:29]
	v_cvt_pk_bf16_f32 v172, v64, v77
	v_add_u32_e32 v64, v99, v100
	v_cndmask_b32_e64 v89, v174, 0, s[30:31]
	v_cndmask_b32_e64 v173, v175, 0, s[34:35]
	v_add_u32_e32 v64, 0xf000, v64
	v_cvt_pk_bf16_f32 v173, v89, v173
	ds_write2_b64 v64, v[90:91], v[176:177] offset0:128 offset1:132
	ds_write2_b64 v64, v[192:193], v[172:173] offset0:136 offset1:140
	ds_write_b128 v127, v[36:39] offset:17408
	ds_write_b128 v127, v[44:47] offset:17424
	ds_write_b128 v127, v[32:35] offset:17552
	ds_write_b128 v127, v[40:43] offset:17568
	v_ashrrev_i32_e32 v40, 8, v147
	v_cmp_gt_i32_e32 vcc, 32, v40
	v_lshlrev_b32_e32 v40, 1, v40
	v_subrev_u32_e32 v42, 63, v40
	v_or_b32_e32 v40, 1, v40
	v_ashrrev_i32_e32 v41, 31, v40
	v_cndmask_b32_e32 v41, 0, v41, vcc
	v_cndmask_b32_e32 v40, v42, v40, vcc
	v_cndmask_b32_e32 v64, v133, v134, vcc
	v_lshl_add_u64 v[42:43], s[94:95], 0, v[64:65]
	v_lshlrev_b64 v[40:41], 20, v[40:41]
	v_add_u32_e32 v46, v99, v96
	v_lshl_add_u64 v[40:41], v[42:43], 0, v[40:41]
	v_and_b32_e32 v42, 0x7f800, v148
	s_waitcnt lgkmcnt(0)
	s_barrier
	s_waitcnt lgkmcnt(0)
	ds_read_b128 v[196:199], v46 offset:62464
	ds_read_b128 v[200:203], v46 offset:62528
	ds_read_b128 v[204:207], v128 offset:35840
	ds_read_b128 v[208:211], v128 offset:35904
	ds_read_b128 v[212:215], v126 offset:45056
	ds_read_b128 v[216:219], v126 offset:45120
	ds_read_b128 v[220:223], v126 offset:45184
	ds_read_b128 v[224:227], v126 offset:45248
	ds_read_b128 v[228:231], v128 offset:38208
	ds_read_b128 v[232:235], v128 offset:38144
	ds_read_b128 v[236:239], v126 offset:49408
	ds_read_b128 v[244:247], v126 offset:49472
	ds_read_b128 v[248:251], v126 offset:49536
	v_lshlrev_b32_e32 v64, 1, v42
	s_waitcnt lgkmcnt(10)
	v_mfma_f32_16x16x32_bf16 v[42:45], v[204:207], v[196:199], 0
	ds_read_b128 v[252:255], v126 offset:49600
	ds_read_b128 v[204:207], v128 offset:40512
	v_lshl_add_u64 v[40:41], v[40:41], 0, v[64:65]
	v_mov_b32_e32 v89, v65
	v_lshl_add_u64 v[40:41], v[40:41], 0, v[88:89]
	s_waitcnt lgkmcnt(11)
	v_mfma_f32_16x16x32_bf16 v[42:45], v[208:211], v[200:203], v[42:45]
	ds_read_b128 v[208:211], v128 offset:40448
	v_lshl_add_u64 v[40:41], v[78:79], 1, v[40:41]
	v_mov_b32_e32 v77, v65
	s_waitcnt lgkmcnt(11)
	v_mfma_f32_16x16x32_bf16 v[42:45], v[212:215], v[60:63], v[42:45]
	ds_read_b128 v[212:215], v126 offset:53760
	v_lshl_add_u64 v[40:41], v[40:41], 0, v[76:77]
	v_add_u32_e32 v148, 0xfffe0000, v148
	s_waitcnt lgkmcnt(11)
	v_mfma_f32_16x16x32_bf16 v[42:45], v[216:219], v[52:55], v[42:45]
	ds_read_b128 v[216:219], v126 offset:53824
	v_subrev_u32_e32 v147, 64, v147
	s_waitcnt lgkmcnt(11)
	v_mfma_f32_16x16x32_bf16 v[42:45], v[220:223], v[56:59], v[42:45]
	ds_read_b128 v[220:223], v126 offset:53888
	s_waitcnt lgkmcnt(11)
	v_mfma_f32_16x16x32_bf16 v[42:45], v[224:227], v[48:51], v[42:45]
	ds_read_b128 v[224:227], v128 offset:42752
	s_nop 6
	v_cvt_pk_bf16_f32 v42, v42, v43
	v_cvt_pk_bf16_f32 v43, v44, v45
	global_store_dwordx2 v[40:41], v[42:43], off
	s_waitcnt lgkmcnt(10)
	v_mfma_f32_16x16x32_bf16 v[42:45], v[232:235], v[196:199], 0
	ds_read_b128 v[232:235], v126 offset:58112
	v_mfma_f32_16x16x32_bf16 v[42:45], v[228:231], v[200:203], v[42:45]
	ds_read_b128 v[228:231], v126 offset:58176
	s_waitcnt lgkmcnt(11)
	v_mfma_f32_16x16x32_bf16 v[42:45], v[236:239], v[60:63], v[42:45]
	ds_read_b128 v[236:239], v126 offset:58240
	s_waitcnt lgkmcnt(11)
	v_mfma_f32_16x16x32_bf16 v[42:45], v[244:247], v[52:55], v[42:45]
	ds_read_b128 v[244:247], v126 offset:58304
	s_waitcnt lgkmcnt(11)
	v_mfma_f32_16x16x32_bf16 v[42:45], v[248:251], v[56:59], v[42:45]
	ds_read_b128 v[248:251], v101
	s_waitcnt lgkmcnt(11)
	v_mfma_f32_16x16x32_bf16 v[42:45], v[252:255], v[48:51], v[42:45]
	ds_read_b128 v[252:255], v128 offset:17408
	s_nop 6
	v_cvt_pk_bf16_f32 v42, v42, v43
	v_cvt_pk_bf16_f32 v43, v44, v45
	global_store_dwordx2 v[40:41], v[42:43], off offset:32
	s_waitcnt lgkmcnt(10)
	v_mfma_f32_16x16x32_bf16 v[42:45], v[208:211], v[196:199], 0
	ds_read_b128 v[208:211], v128 offset:17472
	v_mfma_f32_16x16x32_bf16 v[42:45], v[204:207], v[200:203], v[42:45]
	ds_read_b128 v[204:207], v101 offset:64
	s_waitcnt lgkmcnt(11)
	v_mfma_f32_16x16x32_bf16 v[42:45], v[212:215], v[60:63], v[42:45]
	ds_read_b128 v[212:215], v128 offset:19712
	s_waitcnt lgkmcnt(11)
	v_mfma_f32_16x16x32_bf16 v[42:45], v[216:219], v[52:55], v[42:45]
	ds_read_b128 v[216:219], v128 offset:19776
	s_waitcnt lgkmcnt(11)
	v_mfma_f32_16x16x32_bf16 v[42:45], v[220:223], v[56:59], v[42:45]
	ds_read_b128 v[220:223], v101 offset:128
	ds_read_b128 v[172:175], v126 offset:53952
	s_waitcnt lgkmcnt(0)
	v_mfma_f32_16x16x32_bf16 v[42:45], v[172:175], v[48:51], v[42:45]
	s_nop 7
	v_cvt_pk_bf16_f32 v42, v42, v43
	v_cvt_pk_bf16_f32 v43, v44, v45
	global_store_dwordx2 v[40:41], v[42:43], off offset:64
	v_mfma_f32_16x16x32_bf16 v[36:39], v[224:227], v[196:199], 0
	ds_read_b128 v[196:199], v128 offset:22016
	ds_read_b128 v[224:227], v128 offset:22080
	ds_read_b128 v[42:45], v128 offset:42816
	s_waitcnt lgkmcnt(0)
	v_mfma_f32_16x16x32_bf16 v[32:35], v[42:45], v[200:203], v[36:39]
	s_nop 4
	v_mfma_f32_16x16x32_bf16 v[32:35], v[232:235], v[60:63], v[32:35]
	ds_read_b128 v[200:203], v101 offset:192
	v_mfma_f32_16x16x32_bf16 v[32:35], v[228:231], v[52:55], v[32:35]
	ds_read_b128 v[232:235], v128 offset:24320
	v_mfma_f32_16x16x32_bf16 v[32:35], v[236:239], v[56:59], v[32:35]
	ds_read_b128 v[228:231], v128 offset:24384
	v_mfma_f32_16x16x32_bf16 v[32:35], v[244:247], v[48:51], v[32:35]
	ds_read_b128 v[236:239], v101 offset:256
	s_nop 7
	v_cvt_pk_bf16_f32 v32, v32, v33
	v_cvt_pk_bf16_f32 v33, v34, v35
	global_store_dwordx2 v[40:41], v[32:33], off offset:96
	ds_read_b128 v[36:39], v46 offset:35840
	ds_read_b128 v[32:35], v46 offset:35904
	v_pk_mul_f32 v[4:5], v[4:5], v[248:249]
	ds_read_b128 v[244:247], v128 offset:26624
	v_pk_mul_f32 v[6:7], v[6:7], v[250:251]
	s_waitcnt lgkmcnt(2)
	s_nop 0
	v_mfma_f32_16x16x32_bf16 v[4:7], v[252:255], v[36:39], v[4:7]
	ds_read_b128 v[248:251], v128 offset:26688
	s_waitcnt lgkmcnt(2)
	v_mfma_f32_16x16x32_bf16 v[4:7], v[208:211], v[32:35], v[4:7]
	ds_read_b128 v[252:255], v101 offset:320
	v_pk_mul_f32 v[0:1], v[0:1], v[204:205]
	ds_read_b128 v[208:211], v128 offset:28928
	v_pk_mul_f32 v[2:3], v[2:3], v[206:207]
	s_nop 1
	v_mfma_f32_16x16x32_bf16 v[0:3], v[212:215], v[36:39], v[0:3]
	ds_read_b128 v[204:207], v128 offset:28992
	v_mfma_f32_16x16x32_bf16 v[0:3], v[216:219], v[32:35], v[0:3]
	ds_read_b128 v[212:215], v101 offset:384
	v_pk_mul_f32 v[8:9], v[8:9], v[220:221]
	ds_read_b128 v[216:219], v128 offset:31232
	v_pk_mul_f32 v[10:11], v[10:11], v[222:223]
	s_nop 1
	v_mfma_f32_16x16x32_bf16 v[8:11], v[196:199], v[36:39], v[8:11]
	ds_read_b128 v[220:223], v128 offset:31296
	v_mfma_f32_16x16x32_bf16 v[8:11], v[224:227], v[32:35], v[8:11]
	ds_read_b128 v[196:199], v101 offset:448
	v_pk_mul_f32 v[12:13], v[12:13], v[200:201]
	v_pk_mul_f32 v[14:15], v[14:15], v[202:203]
	s_nop 1
	v_mfma_f32_16x16x32_bf16 v[12:15], v[232:235], v[36:39], v[12:15]
	v_mfma_f32_16x16x32_bf16 v[12:15], v[228:231], v[32:35], v[12:15]
	v_pk_mul_f32 v[16:17], v[16:17], v[236:237]
	v_pk_mul_f32 v[18:19], v[18:19], v[238:239]
	s_waitcnt lgkmcnt(8)
	s_nop 0
	v_mfma_f32_16x16x32_bf16 v[16:19], v[244:247], v[36:39], v[16:19]
	s_waitcnt lgkmcnt(7)
	v_mfma_f32_16x16x32_bf16 v[16:19], v[248:251], v[32:35], v[16:19]
	s_waitcnt lgkmcnt(6)
	v_pk_mul_f32 v[20:21], v[20:21], v[252:253]
	v_pk_mul_f32 v[22:23], v[22:23], v[254:255]
	s_waitcnt lgkmcnt(5)
	s_nop 0
	v_mfma_f32_16x16x32_bf16 v[20:23], v[208:211], v[36:39], v[20:23]
	s_waitcnt lgkmcnt(4)
	v_mfma_f32_16x16x32_bf16 v[20:23], v[204:207], v[32:35], v[20:23]
	s_waitcnt lgkmcnt(3)
	v_pk_mul_f32 v[24:25], v[24:25], v[212:213]
	v_pk_mul_f32 v[26:27], v[26:27], v[214:215]
	s_waitcnt lgkmcnt(2)
	s_nop 0
	v_mfma_f32_16x16x32_bf16 v[24:27], v[216:219], v[36:39], v[24:27]
	s_waitcnt lgkmcnt(1)
	v_mfma_f32_16x16x32_bf16 v[24:27], v[220:223], v[32:35], v[24:27]
	s_waitcnt lgkmcnt(0)
	v_pk_mul_f32 v[28:29], v[28:29], v[196:197]
	v_pk_mul_f32 v[30:31], v[30:31], v[198:199]
	ds_read_b128 v[40:43], v128 offset:33536
	s_waitcnt lgkmcnt(0)
	v_mfma_f32_16x16x32_bf16 v[28:31], v[40:43], v[36:39], v[28:31]
	ds_read_b128 v[36:39], v128 offset:33600
	s_waitcnt lgkmcnt(0)
	s_barrier
	v_mfma_f32_16x16x32_bf16 v[28:31], v[36:39], v[32:35], v[28:31]
	s_cbranch_scc0 .LBB0_1040

.LBB0_1058:
	v_mov_b32_e32 v37, v34
	v_mov_b32_e32 v34, v33
	v_mov_b32_e32 v36, v32
	v_pk_mul_f32 v[32:33], v[76:77], v[34:35]
	v_mov_b32_e32 v34, v38
	v_mov_b32_e32 v35, v40
	v_pk_mul_f32 v[36:37], v[76:77], v[36:37]
	v_pk_mul_f32 v[34:35], v[76:77], v[34:35]
	v_cvt_pk_bf16_f32 v36, v36, v37
	v_mov_b32_e32 v40, v39
	v_cvt_pk_bf16_f32 v37, v34, v35
	v_mov_b32_e32 v34, v42
	v_mov_b32_e32 v35, v44
	v_mov_b32_e32 v44, v43
	v_pk_mul_f32 v[38:39], v[76:77], v[40:41]
	v_pk_mul_f32 v[34:35], v[76:77], v[34:35]
	v_pk_mul_f32 v[40:41], v[76:77], v[44:45]
	v_cvt_pk_bf16_f32 v32, v32, v33
	v_cvt_pk_bf16_f32 v33, v38, v39
	v_cvt_pk_bf16_f32 v38, v34, v35
	v_cvt_pk_bf16_f32 v34, v40, v41
	v_mov_b32_e32 v40, v46
	v_mov_b32_e32 v41, v48
	v_pk_mul_f32 v[40:41], v[76:77], v[40:41]
	v_mov_b32_e32 v48, v47
	v_pk_mul_f32 v[42:43], v[76:77], v[48:49]
	v_cvt_pk_bf16_f32 v39, v40, v41
	v_mov_b32_e32 v40, v50
	v_mov_b32_e32 v41, v52
	v_mov_b32_e32 v52, v51
	v_cvt_pk_bf16_f32 v35, v42, v43
	v_pk_mul_f32 v[40:41], v[76:77], v[40:41]
	v_pk_mul_f32 v[42:43], v[76:77], v[52:53]
	v_cvt_pk_bf16_f32 v44, v40, v41
	v_cvt_pk_bf16_f32 v40, v42, v43
	v_mov_b32_e32 v42, v54
	v_mov_b32_e32 v43, v56
	v_pk_mul_f32 v[42:43], v[76:77], v[42:43]
	v_mov_b32_e32 v56, v55
	v_cvt_pk_bf16_f32 v45, v42, v43
	v_mov_b32_e32 v42, v58
	v_mov_b32_e32 v43, v60
	v_mov_b32_e32 v60, v59
	v_pk_mul_f32 v[46:47], v[76:77], v[56:57]
	v_pk_mul_f32 v[42:43], v[76:77], v[42:43]
	v_pk_mul_f32 v[48:49], v[76:77], v[60:61]
	v_cvt_pk_bf16_f32 v41, v46, v47
	v_cvt_pk_bf16_f32 v46, v42, v43
	v_cvt_pk_bf16_f32 v42, v48, v49
	v_mov_b32_e32 v48, v62
	v_mov_b32_e32 v49, v86
	v_mov_b32_e32 v86, v63
	v_pk_mul_f32 v[48:49], v[76:77], v[48:49]
	v_pk_mul_f32 v[50:51], v[76:77], v[86:87]
	v_cvt_pk_bf16_f32 v47, v48, v49
	v_cvt_pk_bf16_f32 v43, v50, v51
	s_waitcnt lgkmcnt(0)
	s_barrier
	s_waitcnt lgkmcnt(0)
	ds_read_b128 v[196:199], v93
	v_add_u32_e32 v52, v94, v96
	v_add_u32_e32 v60, v94, v91
	s_add_i32 s52, s52, 1
	v_lshl_add_u64 v[78:79], v[78:79], 0, s[48:49]
	s_waitcnt lgkmcnt(0)
	v_pk_mul_f32 v[48:49], v[4:5], v[196:197]
	v_pk_mul_f32 v[50:51], v[6:7], v[198:199]
	v_cvt_pk_bf16_f32 v48, v48, v49
	v_cvt_pk_bf16_f32 v49, v50, v51
	ds_write_b64 v52, v[48:49] offset:45056
	ds_read_b128 v[200:203], v93 offset:64
	v_lshl_add_u64 v[80:81], v[80:81], 0, s[48:49]
	v_lshl_add_u64 v[82:83], v[82:83], 0, s[50:51]
	s_cmp_lg_u32 s52, 32
	s_waitcnt lgkmcnt(0)
	v_pk_mul_f32 v[48:49], v[0:1], v[200:201]
	v_pk_mul_f32 v[50:51], v[2:3], v[202:203]
	v_cvt_pk_bf16_f32 v48, v48, v49
	v_cvt_pk_bf16_f32 v49, v50, v51
	ds_write_b64 v118, v[48:49] offset:45056
	ds_read_b128 v[204:207], v93 offset:128
	s_waitcnt lgkmcnt(0)
	v_pk_mul_f32 v[48:49], v[8:9], v[204:205]
	v_pk_mul_f32 v[50:51], v[10:11], v[206:207]
	v_cvt_pk_bf16_f32 v48, v48, v49
	v_cvt_pk_bf16_f32 v49, v50, v51
	ds_write_b64 v119, v[48:49] offset:45056
	ds_read_b128 v[208:211], v93 offset:192
	s_waitcnt lgkmcnt(0)
	v_pk_mul_f32 v[48:49], v[12:13], v[208:209]
	v_pk_mul_f32 v[50:51], v[14:15], v[210:211]
	v_cvt_pk_bf16_f32 v48, v48, v49
	v_cvt_pk_bf16_f32 v49, v50, v51
	ds_write_b64 v120, v[48:49] offset:45056
	ds_read_b128 v[212:215], v93 offset:256
	s_waitcnt lgkmcnt(0)
	v_pk_mul_f32 v[48:49], v[16:17], v[212:213]
	v_pk_mul_f32 v[50:51], v[18:19], v[214:215]
	v_cvt_pk_bf16_f32 v48, v48, v49
	v_cvt_pk_bf16_f32 v49, v50, v51
	ds_write_b64 v52, v[48:49] offset:45184
	ds_read_b128 v[216:219], v93 offset:320
	s_waitcnt lgkmcnt(0)
	v_pk_mul_f32 v[48:49], v[20:21], v[216:217]
	v_pk_mul_f32 v[50:51], v[22:23], v[218:219]
	v_cvt_pk_bf16_f32 v48, v48, v49
	v_cvt_pk_bf16_f32 v49, v50, v51
	ds_write_b64 v52, v[48:49] offset:45216
	ds_read_b128 v[220:223], v93 offset:384
	s_waitcnt lgkmcnt(0)
	v_pk_mul_f32 v[48:49], v[24:25], v[220:221]
	v_pk_mul_f32 v[50:51], v[26:27], v[222:223]
	v_cvt_pk_bf16_f32 v48, v48, v49
	v_cvt_pk_bf16_f32 v49, v50, v51
	ds_write_b64 v52, v[48:49] offset:45248
	ds_read_b128 v[224:227], v93 offset:448
	s_waitcnt lgkmcnt(0)
	v_pk_mul_f32 v[48:49], v[28:29], v[224:225]
	v_pk_mul_f32 v[50:51], v[30:31], v[226:227]
	v_cvt_pk_bf16_f32 v48, v48, v49
	v_cvt_pk_bf16_f32 v49, v50, v51
	ds_write_b64 v52, v[48:49] offset:45280
	ds_read_b128 v[228:231], v121 offset:17408
	ds_read_b128 v[232:235], v121 offset:17472
	ds_read_b128 v[236:239], v121 offset:17536
	ds_read_b128 v[244:247], v121 offset:17600
	ds_read_b128 v[248:251], v121 offset:21824
	ds_read_b128 v[252:255], v121 offset:21760
	ds_read_b128 v[196:199], v121 offset:21888
	ds_read_b128 v[200:203], v121 offset:21952
	ds_read_b128 v[204:207], v121 offset:26176
	ds_read_b128 v[208:211], v121 offset:26112
	ds_read_b128 v[212:215], v121 offset:26240
	ds_read_b128 v[216:219], v121 offset:26304
	ds_read_b128 v[220:223], v121 offset:30528
	ds_read_b128 v[48:51], v60
	ds_read_b128 v[52:55], v60 offset:64
	ds_read_b128 v[56:59], v60 offset:128
	ds_read_b128 v[60:63], v60 offset:192
	s_waitcnt lgkmcnt(3)
	v_mfma_f32_16x16x32_bf16 v[164:167], v[228:231], v[48:51], 0
	ds_read_b128 v[224:227], v121 offset:30464
	s_waitcnt lgkmcnt(3)
	v_mfma_f32_16x16x32_bf16 v[164:167], v[232:235], v[52:55], v[164:167]
	ds_read_b128 v[228:231], v121 offset:30592
	s_waitcnt lgkmcnt(3)
	v_mfma_f32_16x16x32_bf16 v[164:167], v[236:239], v[56:59], v[164:167]
	s_waitcnt lgkmcnt(2)
	v_mfma_f32_16x16x32_bf16 v[164:167], v[244:247], v[60:63], v[164:167]
	s_nop 6
	s_nop 0
	v_cndmask_b32_e64 v86, v164, 0, s[0:1]
	v_cndmask_b32_e64 v87, 0, v165, s[2:3]
	v_cndmask_b32_e64 v163, v166, 0, s[4:5]
	v_cndmask_b32_e64 v164, v167, 0, s[6:7]
	v_cvt_pk_bf16_f32 v86, v86, v87
	v_cvt_pk_bf16_f32 v87, v163, v164
	v_mfma_f32_16x16x32_bf16 v[164:167], v[252:255], v[48:51], 0
	v_mfma_f32_16x16x32_bf16 v[164:167], v[248:251], v[52:55], v[164:167]
	v_mfma_f32_16x16x32_bf16 v[164:167], v[196:199], v[56:59], v[164:167]
	v_mfma_f32_16x16x32_bf16 v[164:167], v[200:203], v[60:63], v[164:167]
	s_nop 6
	s_nop 0
	v_cndmask_b32_e64 v163, v164, 0, s[8:9]
	v_cndmask_b32_e64 v164, v165, 0, s[10:11]
	v_cndmask_b32_e64 v165, v166, 0, s[12:13]
	v_cndmask_b32_e64 v166, v167, 0, s[14:15]
	v_cvt_pk_bf16_f32 v172, v163, v164
	v_cvt_pk_bf16_f32 v173, v165, v166
	v_mfma_f32_16x16x32_bf16 v[164:167], v[208:211], v[48:51], 0
	v_mfma_f32_16x16x32_bf16 v[164:167], v[204:207], v[52:55], v[164:167]
	v_mfma_f32_16x16x32_bf16 v[164:167], v[212:215], v[56:59], v[164:167]
	v_mfma_f32_16x16x32_bf16 v[164:167], v[216:219], v[60:63], v[164:167]
	s_nop 6
	s_nop 0
	v_cndmask_b32_e64 v163, v164, 0, s[16:17]
	v_cndmask_b32_e64 v164, v165, 0, s[18:19]
	v_cndmask_b32_e64 v165, v166, 0, s[20:21]
	v_cndmask_b32_e64 v166, v167, 0, s[22:23]
	v_cvt_pk_bf16_f32 v174, v163, v164
	v_cvt_pk_bf16_f32 v175, v165, v166
	s_waitcnt lgkmcnt(1)
	v_mfma_f32_16x16x32_bf16 v[164:167], v[224:227], v[48:51], 0
	v_mfma_f32_16x16x32_bf16 v[164:167], v[220:223], v[52:55], v[164:167]
	s_waitcnt lgkmcnt(0)
	v_mfma_f32_16x16x32_bf16 v[164:167], v[228:231], v[56:59], v[164:167]
	ds_read_b128 v[168:171], v121 offset:30656
	s_waitcnt lgkmcnt(0)
	s_barrier
	v_mfma_f32_16x16x32_bf16 v[164:167], v[168:171], v[60:63], v[164:167]
	s_nop 7
	v_cndmask_b32_e64 v163, v164, 0, s[24:25]
	v_cndmask_b32_e64 v164, v165, 0, s[26:27]
	v_cvt_pk_bf16_f32 v164, v163, v164
	v_add_u32_e32 v163, v95, v96
	v_cndmask_b32_e64 v165, v166, 0, s[28:29]
	v_cndmask_b32_e64 v166, v167, 0, s[30:31]
	v_add_u32_e32 v163, 0xf000, v163
	v_cvt_pk_bf16_f32 v165, v165, v166
	ds_write2_b64 v163, v[86:87], v[172:173] offset0:128 offset1:132
	ds_write2_b64 v163, v[174:175], v[164:165] offset0:136 offset1:140
	ds_write_b128 v122, v[36:39] offset:17408
	ds_write_b128 v122, v[44:47] offset:17424
	ds_write_b128 v122, v[32:35] offset:17552
	ds_write_b128 v122, v[40:43] offset:17568
	v_add_u32_e32 v86, v95, v91
	s_waitcnt lgkmcnt(0)
	s_barrier
	s_waitcnt lgkmcnt(0)
	ds_read_b128 v[196:199], v86 offset:62464
	ds_read_b128 v[200:203], v86 offset:62528
	ds_read_b128 v[204:207], v123 offset:35840
	ds_read_b128 v[208:211], v123 offset:35904
	ds_read_b128 v[212:215], v121 offset:45056
	ds_read_b128 v[216:219], v121 offset:45120
	ds_read_b128 v[220:223], v121 offset:45184
	ds_read_b128 v[224:227], v121 offset:45248
	ds_read_b128 v[228:231], v123 offset:38208
	ds_read_b128 v[232:235], v123 offset:38144
	ds_read_b128 v[236:239], v121 offset:49408
	ds_read_b128 v[244:247], v121 offset:49472
	ds_read_b128 v[248:251], v121 offset:49536
	s_waitcnt lgkmcnt(10)
	v_mfma_f32_16x16x32_bf16 v[40:43], v[204:207], v[196:199], 0
	ds_read_b128 v[252:255], v121 offset:49600
	ds_read_b128 v[204:207], v123 offset:40512
	s_waitcnt lgkmcnt(11)
	v_mfma_f32_16x16x32_bf16 v[40:43], v[208:211], v[200:203], v[40:43]
	ds_read_b128 v[208:211], v123 offset:40448
	s_waitcnt lgkmcnt(11)
	v_mfma_f32_16x16x32_bf16 v[40:43], v[212:215], v[48:51], v[40:43]
	ds_read_b128 v[212:215], v121 offset:53760
	s_waitcnt lgkmcnt(11)
	v_mfma_f32_16x16x32_bf16 v[40:43], v[216:219], v[52:55], v[40:43]
	ds_read_b128 v[216:219], v121 offset:53824
	s_waitcnt lgkmcnt(11)
	v_mfma_f32_16x16x32_bf16 v[40:43], v[220:223], v[56:59], v[40:43]
	ds_read_b128 v[220:223], v121 offset:53888
	s_waitcnt lgkmcnt(11)
	v_mfma_f32_16x16x32_bf16 v[40:43], v[224:227], v[60:63], v[40:43]
	ds_read_b128 v[224:227], v123 offset:42752
	s_nop 6
	v_cvt_pk_bf16_f32 v40, v40, v41
	v_cvt_pk_bf16_f32 v41, v42, v43
	global_store_dwordx2 v[84:85], v[40:41], off offset:-64
	s_waitcnt lgkmcnt(10)
	v_mfma_f32_16x16x32_bf16 v[40:43], v[232:235], v[196:199], 0
	ds_read_b128 v[232:235], v123 offset:42816
	v_mfma_f32_16x16x32_bf16 v[40:43], v[228:231], v[200:203], v[40:43]
	ds_read_b128 v[228:231], v121 offset:58112
	s_waitcnt lgkmcnt(11)
	v_mfma_f32_16x16x32_bf16 v[40:43], v[236:239], v[48:51], v[40:43]
	ds_read_b128 v[236:239], v121 offset:58176
	s_waitcnt lgkmcnt(11)
	v_mfma_f32_16x16x32_bf16 v[40:43], v[244:247], v[52:55], v[40:43]
	ds_read_b128 v[244:247], v121 offset:58240
	s_waitcnt lgkmcnt(11)
	v_mfma_f32_16x16x32_bf16 v[40:43], v[248:251], v[56:59], v[40:43]
	ds_read_b128 v[248:251], v121 offset:58304
	s_waitcnt lgkmcnt(11)
	v_mfma_f32_16x16x32_bf16 v[40:43], v[252:255], v[60:63], v[40:43]
	ds_read_b128 v[252:255], v97
	s_nop 6
	v_cvt_pk_bf16_f32 v40, v40, v41
	v_cvt_pk_bf16_f32 v41, v42, v43
	global_store_dwordx2 v[84:85], v[40:41], off offset:-32
	s_waitcnt lgkmcnt(10)
	v_mfma_f32_16x16x32_bf16 v[40:43], v[208:211], v[196:199], 0
	ds_read_b128 v[208:211], v123 offset:17408
	v_mfma_f32_16x16x32_bf16 v[40:43], v[204:207], v[200:203], v[40:43]
	ds_read_b128 v[204:207], v123 offset:17472
	s_waitcnt lgkmcnt(11)
	v_mfma_f32_16x16x32_bf16 v[40:43], v[212:215], v[48:51], v[40:43]
	ds_read_b128 v[212:215], v97 offset:64
	s_waitcnt lgkmcnt(11)
	v_mfma_f32_16x16x32_bf16 v[40:43], v[216:219], v[52:55], v[40:43]
	ds_read_b128 v[216:219], v123 offset:19712
	s_waitcnt lgkmcnt(11)
	v_mfma_f32_16x16x32_bf16 v[40:43], v[220:223], v[56:59], v[40:43]
	ds_read_b128 v[220:223], v123 offset:19776
	ds_read_b128 v[44:47], v121 offset:53952
	s_waitcnt lgkmcnt(0)
	v_mfma_f32_16x16x32_bf16 v[40:43], v[44:47], v[60:63], v[40:43]
	s_nop 7
	v_cvt_pk_bf16_f32 v40, v40, v41
	v_cvt_pk_bf16_f32 v41, v42, v43
	global_store_dwordx2 v[84:85], v[40:41], off
	v_mfma_f32_16x16x32_bf16 v[32:35], v[224:227], v[196:199], 0
	ds_read_b128 v[196:199], v97 offset:128
	ds_read_b128 v[224:227], v123 offset:22016
	v_mfma_f32_16x16x32_bf16 v[32:35], v[232:235], v[200:203], v[32:35]
	ds_read_b128 v[200:203], v123 offset:22080
	v_mfma_f32_16x16x32_bf16 v[32:35], v[228:231], v[48:51], v[32:35]
	ds_read_b128 v[232:235], v97 offset:192
	v_mfma_f32_16x16x32_bf16 v[32:35], v[236:239], v[52:55], v[32:35]
	ds_read_b128 v[228:231], v123 offset:24320
	v_mfma_f32_16x16x32_bf16 v[32:35], v[244:247], v[56:59], v[32:35]
	ds_read_b128 v[236:239], v123 offset:24384
	v_mfma_f32_16x16x32_bf16 v[32:35], v[248:251], v[60:63], v[32:35]
	ds_read_b128 v[244:247], v97 offset:256
	s_nop 7
	v_cvt_pk_bf16_f32 v32, v32, v33
	v_cvt_pk_bf16_f32 v33, v34, v35
	global_store_dwordx2 v[84:85], v[32:33], off offset:32
	ds_read_b128 v[36:39], v86 offset:35840
	ds_read_b128 v[32:35], v86 offset:35904
	v_lshl_add_u64 v[84:85], v[84:85], 0, s[50:51]
	v_pk_mul_f32 v[4:5], v[4:5], v[252:253]
	ds_read_b128 v[248:251], v123 offset:26624
	v_pk_mul_f32 v[6:7], v[6:7], v[254:255]
	s_waitcnt lgkmcnt(2)
	s_nop 0
	v_mfma_f32_16x16x32_bf16 v[4:7], v[208:211], v[36:39], v[4:7]
	ds_read_b128 v[252:255], v123 offset:26688
	s_waitcnt lgkmcnt(2)
	v_mfma_f32_16x16x32_bf16 v[4:7], v[204:207], v[32:35], v[4:7]
	ds_read_b128 v[208:211], v97 offset:320
	v_pk_mul_f32 v[0:1], v[0:1], v[212:213]
	ds_read_b128 v[204:207], v123 offset:28928
	v_pk_mul_f32 v[2:3], v[2:3], v[214:215]
	s_nop 1
	v_mfma_f32_16x16x32_bf16 v[0:3], v[216:219], v[36:39], v[0:3]
	ds_read_b128 v[212:215], v123 offset:28992
	v_mfma_f32_16x16x32_bf16 v[0:3], v[220:223], v[32:35], v[0:3]
	ds_read_b128 v[216:219], v97 offset:384
	v_pk_mul_f32 v[8:9], v[8:9], v[196:197]
	ds_read_b128 v[220:223], v123 offset:31232
	v_pk_mul_f32 v[10:11], v[10:11], v[198:199]
	s_nop 1
	v_mfma_f32_16x16x32_bf16 v[8:11], v[224:227], v[36:39], v[8:11]
	ds_read_b128 v[196:199], v123 offset:31296
	v_mfma_f32_16x16x32_bf16 v[8:11], v[200:203], v[32:35], v[8:11]
	ds_read_b128 v[224:227], v97 offset:448
	v_pk_mul_f32 v[12:13], v[12:13], v[232:233]
	v_pk_mul_f32 v[14:15], v[14:15], v[234:235]
	s_nop 1
	v_mfma_f32_16x16x32_bf16 v[12:15], v[228:231], v[36:39], v[12:15]
	v_mfma_f32_16x16x32_bf16 v[12:15], v[236:239], v[32:35], v[12:15]
	v_pk_mul_f32 v[16:17], v[16:17], v[244:245]
	v_pk_mul_f32 v[18:19], v[18:19], v[246:247]
	s_waitcnt lgkmcnt(8)
	s_nop 0
	v_mfma_f32_16x16x32_bf16 v[16:19], v[248:251], v[36:39], v[16:19]
	s_waitcnt lgkmcnt(7)
	v_mfma_f32_16x16x32_bf16 v[16:19], v[252:255], v[32:35], v[16:19]
	s_waitcnt lgkmcnt(6)
	v_pk_mul_f32 v[20:21], v[20:21], v[208:209]
	v_pk_mul_f32 v[22:23], v[22:23], v[210:211]
	s_waitcnt lgkmcnt(5)
	s_nop 0
	v_mfma_f32_16x16x32_bf16 v[20:23], v[204:207], v[36:39], v[20:23]
	s_waitcnt lgkmcnt(4)
	v_mfma_f32_16x16x32_bf16 v[20:23], v[212:215], v[32:35], v[20:23]
	s_waitcnt lgkmcnt(3)
	v_pk_mul_f32 v[24:25], v[24:25], v[216:217]
	v_pk_mul_f32 v[26:27], v[26:27], v[218:219]
	s_waitcnt lgkmcnt(2)
	s_nop 0
	v_mfma_f32_16x16x32_bf16 v[24:27], v[220:223], v[36:39], v[24:27]
	s_waitcnt lgkmcnt(1)
	v_mfma_f32_16x16x32_bf16 v[24:27], v[196:199], v[32:35], v[24:27]
	s_waitcnt lgkmcnt(0)
	v_pk_mul_f32 v[28:29], v[28:29], v[224:225]
	v_pk_mul_f32 v[30:31], v[30:31], v[226:227]
	ds_read_b128 v[40:43], v123 offset:33536
	s_waitcnt lgkmcnt(0)
	v_mfma_f32_16x16x32_bf16 v[28:31], v[40:43], v[36:39], v[28:31]
	ds_read_b128 v[36:39], v123 offset:33600
	s_waitcnt lgkmcnt(0)
	s_barrier
	v_mfma_f32_16x16x32_bf16 v[28:31], v[36:39], v[32:35], v[28:31]
	s_cbranch_scc0 .LBB0_1052
